# P10 fused final epilogue: the 8 serialized residual load+wait round trips batched (14 loads issued up front into untouched VGPRs, uses renamed, waits recounted)
# speedup vs baseline: 1.0052x; 1.0012x over previous
; __device__ __forceinline__ void unpack8(const u32x4 w, f32x4& a, f32x4& b) { a = (f32x4){bflo(w.x), bfhi(w.x), bflo(w.y), bfhi(w.y)}; b = (f32x4){bflo(w.z), bfhi(w.z), bflo(w.w), bfhi(w.w)}; }
;     __device__ __forceinline__ void fused(Acc& acc, const Unit& u, int wr, int wc, int fr, int fq, LAS unsigned char* lds) const {
;     ...
; #pragma unroll
;         for (int ai = 0; ai < 2; ++ai)
; #pragma unroll
;             for (int m = 0; m < 4; ++m) {
;                 const int rt = ai * HALF + wr * 64 + m * 16 + fr; const int row = u.pm * BM + rt; float s = 0.f;
; #pragma unroll
;                 for (int bj = 0; bj < 2; ++bj) {
;                     const size_t off = (size_t)row * D + u.pn * BM + bj * HALF + wc * 32 + 8 * fq;
;                     f32x4 b0, b1; unpack8(*(const u32x4*)(base + off), b0, b1);
;                     const f32x4 v0 = b0 + acc[ai][bj][m][0] * scale, v1 = b1 + acc[ai][bj][m][1] * scale;
;                     acc[ai][bj][m][0] = v0; acc[ai][bj][m][1] = v1;
;                     s += (v0[0] * v0[0] + v0[1] * v0[1]) + (v0[2] * v0[2] + v0[3] * v0[3]) + (v1[0] * v1[0] + v1[1] * v1[1]) + (v1[2] * v1[2] + v1[3] * v1[3]);
;                 }
;                 s += __shfl_xor(s, 16); s += __shfl_xor(s, 32);
;                 if (fq == 0) Pw[rt * 4 + wc] = s;
.LBB0_1894:
	s_lshl_b32 s8, s10, 8
	v_add_u32_e32 v134, s8, v167
	v_ashrrev_i32_e32 v135, 31, v134
	s_lshl_b32 s2, s12, 8
	v_lshlrev_b64 v[136:137], 11, v[134:135]
	s_ashr_i32 s3, s2, 31
	v_lshl_add_u64 v[136:137], s[40:41], 0, v[136:137]
	s_mov_b32 s1, 0
	v_lshl_add_u64 v[136:137], s[2:3], 1, v[136:137]
	s_lshl_b32 s0, s11, 6
	v_mov_b32_e32 v133, 0
	v_lshl_add_u64 v[136:137], v[136:137], 0, s[0:1]
	v_lshl_add_u64 v[140:141], v[136:137], 0, v[132:133]
	s_waitcnt vmcnt(0)
	s_barrier
	v_mov_b64_e32 v[196:197], v[140:141]
	global_load_dwordx4 v[136:139], v[140:141], off
	s_nop 0
	global_load_dwordx4 v[140:143], v[140:141], off offset:256
	s_mov_b64 s[100:101], 0x8000
	v_lshl_add_u64 v[254:255], v[196:197], 0, s[100:101]
	global_load_dwordx4 v[192:195], v[254:255], off
	global_load_dwordx4 v[200:203], v[254:255], off offset:256
	s_mov_b64 s[100:101], 0x10000
	v_lshl_add_u64 v[254:255], v[196:197], 0, s[100:101]
	global_load_dwordx4 v[204:207], v[254:255], off
	global_load_dwordx4 v[208:211], v[254:255], off offset:256
	s_mov_b64 s[100:101], 0x18000
	v_lshl_add_u64 v[254:255], v[196:197], 0, s[100:101]
	global_load_dwordx4 v[212:215], v[254:255], off
	global_load_dwordx4 v[216:219], v[254:255], off offset:256
	s_mov_b64 s[100:101], 0x40000
	v_lshl_add_u64 v[254:255], v[196:197], 0, s[100:101]
	global_load_dwordx4 v[220:223], v[254:255], off
	global_load_dwordx4 v[224:227], v[254:255], off offset:256
	s_mov_b64 s[100:101], 0x48000
	v_lshl_add_u64 v[254:255], v[196:197], 0, s[100:101]
	global_load_dwordx4 v[228:231], v[254:255], off
	global_load_dwordx4 v[232:235], v[254:255], off offset:256
	s_mov_b64 s[100:101], 0x50000
	v_lshl_add_u64 v[254:255], v[196:197], 0, s[100:101]
	global_load_dwordx4 v[236:239], v[254:255], off
	global_load_dwordx4 v[240:243], v[254:255], off offset:256
	s_mov_b64 s[100:101], 0x58000
	v_lshl_add_u64 v[254:255], v[196:197], 0, s[100:101]
	global_load_dwordx4 v[244:247], v[254:255], off
	global_load_dwordx4 v[248:251], v[254:255], off offset:256
	v_mbcnt_lo_u32_b32 v132, -1, 0
	v_mbcnt_hi_u32_b32 v132, -1, v132
	v_and_b32_e32 v145, 64, v132
	v_xor_b32_e32 v144, 16, v132
	v_add_u32_e32 v152, 64, v145
	v_cmp_lt_i32_e32 vcc, v144, v152
	s_lshl_b32 s0, s11, 2
	v_lshlrev_b32_e32 v164, 3, v154
	v_cndmask_b32_e32 v144, v132, v144, vcc
	v_lshlrev_b32_e32 v165, 2, v144
	s_lshl_b32 s22, s11, 5
	s_add_i32 s9, s0, 0
	s_waitcnt vmcnt(14)
	v_lshlrev_b32_e32 v144, 16, v136
	v_and_b32_e32 v145, 0xffff0000, v136
	v_lshlrev_b32_e32 v136, 16, v137
	v_and_b32_e32 v137, 0xffff0000, v137
	v_lshlrev_b32_e32 v148, 16, v140
	v_and_b32_e32 v149, 0xffff0000, v140
	v_lshlrev_b32_e32 v140, 16, v141
	v_and_b32_e32 v141, 0xffff0000, v141
	v_lshlrev_b32_e32 v146, 16, v138
	v_and_b32_e32 v147, 0xffff0000, v138
	v_lshlrev_b32_e32 v150, 16, v142
	v_and_b32_e32 v151, 0xffff0000, v142
	v_pk_fma_f32 v[128:129], v[128:129], 0.5, v[136:137] op_sel_hi:[1,0,1]
	v_pk_fma_f32 v[126:127], v[126:127], 0.5, v[144:145] op_sel_hi:[1,0,1]
	v_pk_fma_f32 v[120:121], v[120:121], 0.5, v[140:141] op_sel_hi:[1,0,1]
	v_pk_fma_f32 v[118:119], v[118:119], 0.5, v[148:149] op_sel_hi:[1,0,1]
	v_lshlrev_b32_e32 v138, 16, v139
	v_and_b32_e32 v139, 0xffff0000, v139
	v_lshlrev_b32_e32 v142, 16, v143
	v_and_b32_e32 v143, 0xffff0000, v143
	v_pk_fma_f32 v[122:123], v[122:123], 0.5, v[146:147] op_sel_hi:[1,0,1]
	v_pk_fma_f32 v[114:115], v[114:115], 0.5, v[150:151] op_sel_hi:[1,0,1]
	v_mul_f32_e32 v136, v127, v127
	v_mul_f32_e32 v137, v129, v129
	v_mul_f32_e32 v140, v119, v119
	v_mul_f32_e32 v141, v121, v121
	v_pk_fma_f32 v[124:125], v[124:125], 0.5, v[138:139] op_sel_hi:[1,0,1]
	v_pk_fma_f32 v[116:117], v[116:117], 0.5, v[142:143] op_sel_hi:[1,0,1]
	v_mul_f32_e32 v138, v123, v123
	v_mul_f32_e32 v142, v115, v115
	v_fmac_f32_e32 v136, v126, v126
	v_fmac_f32_e32 v137, v128, v128
	v_fmac_f32_e32 v140, v118, v118
	v_fmac_f32_e32 v141, v120, v120
	v_mul_f32_e32 v139, v125, v125
	v_mul_f32_e32 v143, v117, v117
	v_fmac_f32_e32 v138, v122, v122
	v_fmac_f32_e32 v142, v114, v114
	v_add_f32_e32 v136, v136, v137
	v_add_f32_e32 v137, v140, v141
	v_fmac_f32_e32 v139, v124, v124
	v_fmac_f32_e32 v143, v116, v116
	v_add_f32_e32 v136, v138, v136
	v_add_f32_e32 v137, v142, v137
	v_add_f32_e32 v136, v139, v136
	v_add_f32_e32 v137, v143, v137
	v_add_f32_e32 v136, v136, v137
	ds_bpermute_b32 v137, v165, v136
	v_xor_b32_e32 v138, 32, v132
	v_cmp_lt_i32_e32 vcc, v138, v152
	s_nop 1
	v_cndmask_b32_e32 v132, v132, v138, vcc
	v_lshlrev_b32_e32 v168, 2, v132
	s_waitcnt lgkmcnt(0)
	v_add_f32_e32 v132, v136, v137
	ds_bpermute_b32 v136, v168, v132
	v_cmp_eq_u32_e32 vcc, 0, v154
	s_and_saveexec_b64 s[6:7], vcc
	s_cbranch_execz .LBB0_1896
	v_lshl_add_u32 v137, v167, 4, s9
	s_waitcnt lgkmcnt(0)
	v_add_f32_e32 v132, v132, v136
	ds_write_b32 v137, v132
; __device__ __forceinline__ void unpack8(const u32x4 w, f32x4& a, f32x4& b) { a = (f32x4){bflo(w.x), bfhi(w.x), bflo(w.y), bfhi(w.y)}; b = (f32x4){bflo(w.z), bfhi(w.z), bflo(w.w), bfhi(w.w)}; }
;     __device__ __forceinline__ void fused(Acc& acc, const Unit& u, int wr, int wc, int fr, int fq, LAS unsigned char* lds) const {
;     ...
;                 const int rt = ai * HALF + wr * 64 + m * 16 + fr; const int row = u.pm * BM + rt; float s = 0.f;
; #pragma unroll
;                 for (int bj = 0; bj < 2; ++bj) {
;                     const size_t off = (size_t)row * D + u.pn * BM + bj * HALF + wc * 32 + 8 * fq;
;                     f32x4 b0, b1; unpack8(*(const u32x4*)(base + off), b0, b1);
;                     const f32x4 v0 = b0 + acc[ai][bj][m][0] * scale, v1 = b1 + acc[ai][bj][m][1] * scale;
;                     acc[ai][bj][m][0] = v0; acc[ai][bj][m][1] = v1;
;                     s += (v0[0] * v0[0] + v0[1] * v0[1]) + (v0[2] * v0[2] + v0[3] * v0[3]) + (v1[0] * v1[0] + v1[1] * v1[1]) + (v1[2] * v1[2] + v1[3] * v1[3]);
;                 }
;                 s += __shfl_xor(s, 16); s += __shfl_xor(s, 32);
;                 if (fq == 0) Pw[rt * 4 + wc] = s;
.LBB0_1896:
	s_or_b64 exec, exec, s[6:7]
	v_or_b32_e32 v138, 16, v167
	s_waitcnt lgkmcnt(0)
	v_add_u32_e32 v136, s8, v138
	v_ashrrev_i32_e32 v137, 31, v136
	v_lshlrev_b64 v[140:141], 11, v[136:137]
	v_lshl_add_u64 v[140:141], s[40:41], 0, v[140:141]
	v_lshl_add_u64 v[140:141], s[2:3], 1, v[140:141]
	s_lshl_b32 s0, s22, 1
	v_lshl_add_u64 v[140:141], v[140:141], 0, s[0:1]
	v_lshlrev_b32_e32 v132, 1, v164
	v_lshl_add_u64 v[144:145], v[140:141], 0, v[132:133]
	s_nop 0
	s_waitcnt vmcnt(13)
	v_lshlrev_b32_e32 v148, 16, v192
	v_and_b32_e32 v149, 0xffff0000, v192
	v_lshlrev_b32_e32 v140, 16, v193
	v_and_b32_e32 v141, 0xffff0000, v193
	s_waitcnt vmcnt(12)
	v_lshlrev_b32_e32 v152, 16, v200
	v_and_b32_e32 v153, 0xffff0000, v200
	v_lshlrev_b32_e32 v144, 16, v201
	v_and_b32_e32 v145, 0xffff0000, v201
	v_lshlrev_b32_e32 v150, 16, v194
	v_and_b32_e32 v151, 0xffff0000, v194
	v_lshlrev_b32_e32 v142, 16, v195
	v_and_b32_e32 v143, 0xffff0000, v195
	v_lshlrev_b32_e32 v154, 16, v202
	v_and_b32_e32 v155, 0xffff0000, v202
	v_pk_fma_f32 v[112:113], v[112:113], 0.5, v[140:141] op_sel_hi:[1,0,1]
	v_pk_fma_f32 v[110:111], v[110:111], 0.5, v[148:149] op_sel_hi:[1,0,1]
	v_pk_fma_f32 v[104:105], v[104:105], 0.5, v[144:145] op_sel_hi:[1,0,1]
	v_pk_fma_f32 v[102:103], v[102:103], 0.5, v[152:153] op_sel_hi:[1,0,1]
	v_lshlrev_b32_e32 v146, 16, v203
	v_and_b32_e32 v147, 0xffff0000, v203
	v_pk_fma_f32 v[108:109], v[108:109], 0.5, v[142:143] op_sel_hi:[1,0,1]
	v_pk_fma_f32 v[106:107], v[106:107], 0.5, v[150:151] op_sel_hi:[1,0,1]
	v_pk_fma_f32 v[98:99], v[98:99], 0.5, v[154:155] op_sel_hi:[1,0,1]
	v_mul_f32_e32 v133, v111, v111
	v_mul_f32_e32 v139, v113, v113
	v_mul_f32_e32 v142, v103, v103
	v_mul_f32_e32 v143, v105, v105
	v_pk_fma_f32 v[100:101], v[100:101], 0.5, v[146:147] op_sel_hi:[1,0,1]
	v_mul_f32_e32 v140, v107, v107
	v_mul_f32_e32 v144, v99, v99
	v_fmac_f32_e32 v133, v110, v110
	v_fmac_f32_e32 v139, v112, v112
	v_fmac_f32_e32 v142, v102, v102
	v_fmac_f32_e32 v143, v104, v104
	v_mul_f32_e32 v141, v109, v109
	v_mul_f32_e32 v145, v101, v101
	v_fmac_f32_e32 v140, v106, v106
	v_fmac_f32_e32 v144, v98, v98
	v_add_f32_e32 v133, v133, v139
	v_add_f32_e32 v139, v142, v143
	v_fmac_f32_e32 v141, v108, v108
	v_fmac_f32_e32 v145, v100, v100
	v_add_f32_e32 v133, v140, v133
	v_add_f32_e32 v139, v144, v139
	v_add_f32_e32 v133, v141, v133
	v_add_f32_e32 v139, v145, v139
	v_add_f32_e32 v133, v133, v139
	ds_bpermute_b32 v139, v165, v133
	s_waitcnt lgkmcnt(0)
	v_add_f32_e32 v133, v133, v139
	ds_bpermute_b32 v139, v168, v133
	s_and_saveexec_b64 s[6:7], vcc
	s_cbranch_execz .LBB0_1898
	v_lshl_add_u32 v138, v138, 4, s9
	s_waitcnt lgkmcnt(0)
	v_add_f32_e32 v133, v133, v139
	ds_write_b32 v138, v133
.LBB0_1898:
	s_or_b64 exec, exec, s[6:7]
	v_or_b32_e32 v142, 32, v167
	v_add_u32_e32 v138, s8, v142
	s_waitcnt lgkmcnt(0)
	v_ashrrev_i32_e32 v139, 31, v138
	v_lshlrev_b64 v[140:141], 11, v[138:139]
	v_lshl_add_u64 v[140:141], s[40:41], 0, v[140:141]
	v_lshl_add_u64 v[140:141], s[2:3], 1, v[140:141]
	v_lshl_add_u64 v[140:141], v[140:141], 0, s[0:1]
	v_mov_b32_e32 v133, 0
	v_lshl_add_u64 v[140:141], v[140:141], 0, v[132:133]
	s_waitcnt vmcnt(11)
	v_lshlrev_b32_e32 v140, 16, v204
	v_and_b32_e32 v141, 0xffff0000, v204
	v_lshlrev_b32_e32 v144, 16, v205
	v_and_b32_e32 v145, 0xffff0000, v205
	v_lshlrev_b32_e32 v152, 16, v206
	v_and_b32_e32 v153, 0xffff0000, v206
	s_waitcnt vmcnt(10)
	v_lshlrev_b32_e32 v154, 16, v208
	v_and_b32_e32 v155, 0xffff0000, v208
	v_lshlrev_b32_e32 v148, 16, v209
	v_and_b32_e32 v149, 0xffff0000, v209
	v_lshlrev_b32_e32 v146, 16, v207
	v_and_b32_e32 v147, 0xffff0000, v207
	v_lshlrev_b32_e32 v156, 16, v210
	v_and_b32_e32 v157, 0xffff0000, v210
	v_pk_fma_f32 v[96:97], v[96:97], 0.5, v[144:145] op_sel_hi:[1,0,1]
	v_pk_fma_f32 v[140:141], v[94:95], 0.5, v[140:141] op_sel_hi:[1,0,1]
	v_pk_fma_f32 v[94:95], v[90:91], 0.5, v[152:153] op_sel_hi:[1,0,1]
	v_pk_fma_f32 v[88:89], v[88:89], 0.5, v[148:149] op_sel_hi:[1,0,1]
	v_pk_fma_f32 v[90:91], v[86:87], 0.5, v[154:155] op_sel_hi:[1,0,1]
	v_lshlrev_b32_e32 v150, 16, v211
	v_and_b32_e32 v151, 0xffff0000, v211
	v_pk_fma_f32 v[92:93], v[92:93], 0.5, v[146:147] op_sel_hi:[1,0,1]
	v_pk_fma_f32 v[86:87], v[82:83], 0.5, v[156:157] op_sel_hi:[1,0,1]
	v_mul_f32_e32 v82, v141, v141
	v_mul_f32_e32 v83, v97, v97
	v_mul_f32_e32 v145, v91, v91
	v_mul_f32_e32 v146, v89, v89
	v_pk_fma_f32 v[84:85], v[84:85], 0.5, v[150:151] op_sel_hi:[1,0,1]
	v_mul_f32_e32 v143, v95, v95
	v_mul_f32_e32 v147, v87, v87
	v_fmac_f32_e32 v82, v140, v140
	v_fmac_f32_e32 v83, v96, v96
	v_fmac_f32_e32 v145, v90, v90
	v_fmac_f32_e32 v146, v88, v88
	v_mul_f32_e32 v144, v93, v93
	v_mul_f32_e32 v148, v85, v85
	v_fmac_f32_e32 v143, v94, v94
	v_fmac_f32_e32 v147, v86, v86
	v_add_f32_e32 v82, v82, v83
	v_add_f32_e32 v83, v145, v146
	v_fmac_f32_e32 v144, v92, v92
	v_fmac_f32_e32 v148, v84, v84
	v_add_f32_e32 v82, v143, v82
	v_add_f32_e32 v83, v147, v83
	v_add_f32_e32 v82, v144, v82
	v_add_f32_e32 v83, v148, v83
	v_add_f32_e32 v82, v82, v83
	ds_bpermute_b32 v83, v165, v82
	s_waitcnt lgkmcnt(0)
	v_add_f32_e32 v82, v82, v83
	ds_bpermute_b32 v83, v168, v82
	s_and_saveexec_b64 s[6:7], vcc
	s_cbranch_execz .LBB0_1900
	v_lshl_add_u32 v142, v142, 4, s9
	s_waitcnt lgkmcnt(0)
	v_add_f32_e32 v82, v82, v83
	ds_write_b32 v142, v82
; __device__ __forceinline__ void unpack8(const u32x4 w, f32x4& a, f32x4& b) { a = (f32x4){bflo(w.x), bfhi(w.x), bflo(w.y), bfhi(w.y)}; b = (f32x4){bflo(w.z), bfhi(w.z), bflo(w.w), bfhi(w.w)}; }
;     __device__ __forceinline__ void fused(Acc& acc, const Unit& u, int wr, int wc, int fr, int fq, LAS unsigned char* lds) const {
;     ...
;         for (int ai = 0; ai < 2; ++ai)
; #pragma unroll
;             for (int m = 0; m < 4; ++m) {
;                 const int rt = ai * HALF + wr * 64 + m * 16 + fr; const int row = u.pm * BM + rt; float s = 0.f;
; #pragma unroll
;                 for (int bj = 0; bj < 2; ++bj) {
;                     const size_t off = (size_t)row * D + u.pn * BM + bj * HALF + wc * 32 + 8 * fq;
;                     f32x4 b0, b1; unpack8(*(const u32x4*)(base + off), b0, b1);
;                     const f32x4 v0 = b0 + acc[ai][bj][m][0] * scale, v1 = b1 + acc[ai][bj][m][1] * scale;
;                     acc[ai][bj][m][0] = v0; acc[ai][bj][m][1] = v1;
;                     s += (v0[0] * v0[0] + v0[1] * v0[1]) + (v0[2] * v0[2] + v0[3] * v0[3]) + (v1[0] * v1[0] + v1[1] * v1[1]) + (v1[2] * v1[2] + v1[3] * v1[3]);
;                 }
;                 s += __shfl_xor(s, 16); s += __shfl_xor(s, 32);
;                 if (fq == 0) Pw[rt * 4 + wc] = s;
;             }
.LBB0_1900:
	s_or_b64 exec, exec, s[6:7]
	v_or_b32_e32 v142, 48, v167
	v_add_u32_e32 v82, s8, v142
	s_waitcnt lgkmcnt(0)
	v_ashrrev_i32_e32 v83, 31, v82
	v_lshlrev_b64 v[144:145], 11, v[82:83]
	v_lshl_add_u64 v[144:145], s[40:41], 0, v[144:145]
	v_lshl_add_u64 v[144:145], s[2:3], 1, v[144:145]
	v_lshl_add_u64 v[144:145], v[144:145], 0, s[0:1]
	v_lshl_add_u64 v[148:149], v[144:145], 0, v[132:133]
	s_nop 0
	s_waitcnt vmcnt(9)
	v_lshlrev_b32_e32 v152, 16, v212
	v_and_b32_e32 v153, 0xffff0000, v212
	v_lshlrev_b32_e32 v144, 16, v213
	v_and_b32_e32 v145, 0xffff0000, v213
	s_waitcnt vmcnt(8)
	v_lshlrev_b32_e32 v156, 16, v216
	v_and_b32_e32 v157, 0xffff0000, v216
	v_lshlrev_b32_e32 v148, 16, v217
	v_and_b32_e32 v149, 0xffff0000, v217
	v_lshlrev_b32_e32 v154, 16, v214
	v_and_b32_e32 v155, 0xffff0000, v214
	v_lshlrev_b32_e32 v146, 16, v215
	v_and_b32_e32 v147, 0xffff0000, v215
	v_lshlrev_b32_e32 v158, 16, v218
	v_and_b32_e32 v159, 0xffff0000, v218
	v_pk_fma_f32 v[80:81], v[80:81], 0.5, v[144:145] op_sel_hi:[1,0,1]
	v_pk_fma_f32 v[78:79], v[78:79], 0.5, v[152:153] op_sel_hi:[1,0,1]
	v_pk_fma_f32 v[72:73], v[72:73], 0.5, v[148:149] op_sel_hi:[1,0,1]
	v_pk_fma_f32 v[70:71], v[70:71], 0.5, v[156:157] op_sel_hi:[1,0,1]
	v_lshlrev_b32_e32 v150, 16, v219
	v_and_b32_e32 v151, 0xffff0000, v219
	v_pk_fma_f32 v[76:77], v[76:77], 0.5, v[146:147] op_sel_hi:[1,0,1]
	v_pk_fma_f32 v[74:75], v[74:75], 0.5, v[154:155] op_sel_hi:[1,0,1]
	v_pk_fma_f32 v[66:67], v[66:67], 0.5, v[158:159] op_sel_hi:[1,0,1]
	v_mul_f32_e32 v133, v79, v79
	v_mul_f32_e32 v143, v81, v81
	v_mul_f32_e32 v146, v71, v71
	v_mul_f32_e32 v147, v73, v73
	v_pk_fma_f32 v[68:69], v[68:69], 0.5, v[150:151] op_sel_hi:[1,0,1]
	v_mul_f32_e32 v144, v75, v75
	v_mul_f32_e32 v148, v67, v67
	v_fmac_f32_e32 v133, v78, v78
	v_fmac_f32_e32 v143, v80, v80
	v_fmac_f32_e32 v146, v70, v70
	v_fmac_f32_e32 v147, v72, v72
	v_mul_f32_e32 v145, v77, v77
	v_mul_f32_e32 v149, v69, v69
	v_fmac_f32_e32 v144, v74, v74
	v_fmac_f32_e32 v148, v66, v66
	v_add_f32_e32 v133, v133, v143
	v_add_f32_e32 v143, v146, v147
	v_fmac_f32_e32 v145, v76, v76
	v_fmac_f32_e32 v149, v68, v68
	v_add_f32_e32 v133, v144, v133
	v_add_f32_e32 v143, v148, v143
	v_add_f32_e32 v133, v145, v133
	v_add_f32_e32 v143, v149, v143
	v_add_f32_e32 v133, v133, v143
	ds_bpermute_b32 v143, v165, v133
	s_waitcnt lgkmcnt(0)
	v_add_f32_e32 v133, v133, v143
	ds_bpermute_b32 v143, v168, v133
	s_and_saveexec_b64 s[6:7], vcc
	s_cbranch_execz .LBB0_1902
	v_lshl_add_u32 v142, v142, 4, s9
	s_waitcnt lgkmcnt(0)
	v_add_f32_e32 v133, v133, v143
	ds_write_b32 v142, v133
.LBB0_1902:
	s_or_b64 exec, exec, s[6:7]
	v_add_u32_e32 v144, 0x80, v167
	v_add_u32_e32 v142, s8, v144
	s_waitcnt lgkmcnt(0)
	v_ashrrev_i32_e32 v143, 31, v142
	v_lshlrev_b64 v[146:147], 11, v[142:143]
	v_lshl_add_u64 v[146:147], s[40:41], 0, v[146:147]
	v_lshl_add_u64 v[146:147], s[2:3], 1, v[146:147]
	v_lshl_add_u64 v[146:147], v[146:147], 0, s[0:1]
	v_mov_b32_e32 v133, 0
	v_lshl_add_u64 v[150:151], v[146:147], 0, v[132:133]
	s_nop 0
	s_waitcnt vmcnt(7)
	v_lshlrev_b32_e32 v154, 16, v220
	v_and_b32_e32 v155, 0xffff0000, v220
	v_lshlrev_b32_e32 v146, 16, v221
	v_and_b32_e32 v147, 0xffff0000, v221
	s_waitcnt vmcnt(6)
	v_lshlrev_b32_e32 v158, 16, v224
	v_and_b32_e32 v159, 0xffff0000, v224
	v_lshlrev_b32_e32 v150, 16, v225
	v_and_b32_e32 v151, 0xffff0000, v225
	v_lshlrev_b32_e32 v156, 16, v222
	v_and_b32_e32 v157, 0xffff0000, v222
	v_lshlrev_b32_e32 v148, 16, v223
	v_and_b32_e32 v149, 0xffff0000, v223
	v_lshlrev_b32_e32 v160, 16, v226
	v_and_b32_e32 v161, 0xffff0000, v226
	v_pk_fma_f32 v[64:65], v[64:65], 0.5, v[146:147] op_sel_hi:[1,0,1]
	v_pk_fma_f32 v[62:63], v[62:63], 0.5, v[154:155] op_sel_hi:[1,0,1]
	v_pk_fma_f32 v[56:57], v[56:57], 0.5, v[150:151] op_sel_hi:[1,0,1]
	v_pk_fma_f32 v[54:55], v[54:55], 0.5, v[158:159] op_sel_hi:[1,0,1]
	v_lshlrev_b32_e32 v152, 16, v227
	v_and_b32_e32 v153, 0xffff0000, v227
	v_pk_fma_f32 v[60:61], v[60:61], 0.5, v[148:149] op_sel_hi:[1,0,1]
	v_pk_fma_f32 v[58:59], v[58:59], 0.5, v[156:157] op_sel_hi:[1,0,1]
	v_pk_fma_f32 v[50:51], v[50:51], 0.5, v[160:161] op_sel_hi:[1,0,1]
	v_mul_f32_e32 v145, v63, v63
	v_mul_f32_e32 v146, v65, v65
	v_mul_f32_e32 v149, v55, v55
	v_mul_f32_e32 v150, v57, v57
	v_pk_fma_f32 v[52:53], v[52:53], 0.5, v[152:153] op_sel_hi:[1,0,1]
	v_mul_f32_e32 v147, v59, v59
	v_mul_f32_e32 v151, v51, v51
	v_fmac_f32_e32 v145, v62, v62
	v_fmac_f32_e32 v146, v64, v64
	v_fmac_f32_e32 v149, v54, v54
	v_fmac_f32_e32 v150, v56, v56
	v_mul_f32_e32 v148, v61, v61
	v_mul_f32_e32 v152, v53, v53
	v_fmac_f32_e32 v147, v58, v58
	v_fmac_f32_e32 v151, v50, v50
	v_add_f32_e32 v145, v145, v146
	v_add_f32_e32 v146, v149, v150
	v_fmac_f32_e32 v148, v60, v60
	v_fmac_f32_e32 v152, v52, v52
	v_add_f32_e32 v145, v147, v145
	v_add_f32_e32 v146, v151, v146
	v_add_f32_e32 v145, v148, v145
	v_add_f32_e32 v146, v152, v146
	v_add_f32_e32 v145, v145, v146
	ds_bpermute_b32 v146, v165, v145
	s_waitcnt lgkmcnt(0)
	v_add_f32_e32 v145, v145, v146
	ds_bpermute_b32 v146, v168, v145
	s_and_saveexec_b64 s[6:7], vcc
	s_cbranch_execz .LBB0_1904
	v_lshl_add_u32 v144, v144, 4, s9
	s_waitcnt lgkmcnt(0)
	v_add_f32_e32 v145, v145, v146
	ds_write_b32 v144, v145
; __device__ __forceinline__ void unpack8(const u32x4 w, f32x4& a, f32x4& b) { a = (f32x4){bflo(w.x), bfhi(w.x), bflo(w.y), bfhi(w.y)}; b = (f32x4){bflo(w.z), bfhi(w.z), bflo(w.w), bfhi(w.w)}; }
;     __device__ __forceinline__ void fused(Acc& acc, const Unit& u, int wr, int wc, int fr, int fq, LAS unsigned char* lds) const {
;     ...
;         for (int ai = 0; ai < 2; ++ai)
; #pragma unroll
;             for (int m = 0; m < 4; ++m) {
;                 const int rt = ai * HALF + wr * 64 + m * 16 + fr; const int row = u.pm * BM + rt; float s = 0.f;
; #pragma unroll
;                 for (int bj = 0; bj < 2; ++bj) {
;                     const size_t off = (size_t)row * D + u.pn * BM + bj * HALF + wc * 32 + 8 * fq;
;                     f32x4 b0, b1; unpack8(*(const u32x4*)(base + off), b0, b1);
;                     const f32x4 v0 = b0 + acc[ai][bj][m][0] * scale, v1 = b1 + acc[ai][bj][m][1] * scale;
;                     acc[ai][bj][m][0] = v0; acc[ai][bj][m][1] = v1;
;                     s += (v0[0] * v0[0] + v0[1] * v0[1]) + (v0[2] * v0[2] + v0[3] * v0[3]) + (v1[0] * v1[0] + v1[1] * v1[1]) + (v1[2] * v1[2] + v1[3] * v1[3]);
;                 }
;                 s += __shfl_xor(s, 16); s += __shfl_xor(s, 32);
;                 if (fq == 0) Pw[rt * 4 + wc] = s;
;             }
.LBB0_1904:
	s_or_b64 exec, exec, s[6:7]
	s_waitcnt lgkmcnt(0)
	v_add_u32_e32 v146, 0x90, v167
	v_add_u32_e32 v144, s8, v146
	v_ashrrev_i32_e32 v145, 31, v144
	v_lshlrev_b64 v[148:149], 11, v[144:145]
	v_lshl_add_u64 v[148:149], s[40:41], 0, v[148:149]
	v_lshl_add_u64 v[148:149], s[2:3], 1, v[148:149]
	v_lshl_add_u64 v[148:149], v[148:149], 0, s[0:1]
	v_lshl_add_u64 v[152:153], v[148:149], 0, v[132:133]
	s_nop 0
	s_waitcnt vmcnt(5)
	v_lshlrev_b32_e32 v156, 16, v228
	v_and_b32_e32 v157, 0xffff0000, v228
	v_lshlrev_b32_e32 v148, 16, v229
	v_and_b32_e32 v149, 0xffff0000, v229
	s_waitcnt vmcnt(4)
	v_lshlrev_b32_e32 v160, 16, v232
	v_and_b32_e32 v161, 0xffff0000, v232
	v_lshlrev_b32_e32 v152, 16, v233
	v_and_b32_e32 v153, 0xffff0000, v233
	v_lshlrev_b32_e32 v158, 16, v230
	v_and_b32_e32 v159, 0xffff0000, v230
	v_lshlrev_b32_e32 v150, 16, v231
	v_and_b32_e32 v151, 0xffff0000, v231
	v_lshlrev_b32_e32 v162, 16, v234
	v_and_b32_e32 v163, 0xffff0000, v234
	v_pk_fma_f32 v[48:49], v[48:49], 0.5, v[148:149] op_sel_hi:[1,0,1]
	v_pk_fma_f32 v[46:47], v[46:47], 0.5, v[156:157] op_sel_hi:[1,0,1]
	v_pk_fma_f32 v[40:41], v[40:41], 0.5, v[152:153] op_sel_hi:[1,0,1]
	v_pk_fma_f32 v[38:39], v[38:39], 0.5, v[160:161] op_sel_hi:[1,0,1]
	v_lshlrev_b32_e32 v154, 16, v235
	v_and_b32_e32 v155, 0xffff0000, v235
	v_pk_fma_f32 v[44:45], v[44:45], 0.5, v[150:151] op_sel_hi:[1,0,1]
	v_pk_fma_f32 v[42:43], v[42:43], 0.5, v[158:159] op_sel_hi:[1,0,1]
	v_pk_fma_f32 v[34:35], v[34:35], 0.5, v[162:163] op_sel_hi:[1,0,1]
	v_mul_f32_e32 v133, v47, v47
	v_mul_f32_e32 v147, v49, v49
	v_mul_f32_e32 v150, v39, v39
	v_mul_f32_e32 v151, v41, v41
	v_pk_fma_f32 v[36:37], v[36:37], 0.5, v[154:155] op_sel_hi:[1,0,1]
	v_mul_f32_e32 v148, v43, v43
	v_mul_f32_e32 v152, v35, v35
	v_fmac_f32_e32 v133, v46, v46
	v_fmac_f32_e32 v147, v48, v48
	v_fmac_f32_e32 v150, v38, v38
	v_fmac_f32_e32 v151, v40, v40
	v_mul_f32_e32 v149, v45, v45
	v_mul_f32_e32 v153, v37, v37
	v_fmac_f32_e32 v148, v42, v42
	v_fmac_f32_e32 v152, v34, v34
	v_add_f32_e32 v133, v133, v147
	v_add_f32_e32 v147, v150, v151
	v_fmac_f32_e32 v149, v44, v44
	v_fmac_f32_e32 v153, v36, v36
	v_add_f32_e32 v133, v148, v133
	v_add_f32_e32 v147, v152, v147
	v_add_f32_e32 v133, v149, v133
	v_add_f32_e32 v147, v153, v147
	v_add_f32_e32 v133, v133, v147
	ds_bpermute_b32 v147, v165, v133
	s_waitcnt lgkmcnt(0)
	v_add_f32_e32 v133, v133, v147
	ds_bpermute_b32 v147, v168, v133
	s_and_saveexec_b64 s[6:7], vcc
	s_cbranch_execz .LBB0_1906
	v_lshl_add_u32 v146, v146, 4, s9
	s_waitcnt lgkmcnt(0)
	v_add_f32_e32 v133, v133, v147
	ds_write_b32 v146, v133
; __device__ __forceinline__ void unpack8(const u32x4 w, f32x4& a, f32x4& b) { a = (f32x4){bflo(w.x), bfhi(w.x), bflo(w.y), bfhi(w.y)}; b = (f32x4){bflo(w.z), bfhi(w.z), bflo(w.w), bfhi(w.w)}; }
;     __device__ __forceinline__ void fused(Acc& acc, const Unit& u, int wr, int wc, int fr, int fq, LAS unsigned char* lds) const {
;     ...
;         for (int ai = 0; ai < 2; ++ai)
; #pragma unroll
;             for (int m = 0; m < 4; ++m) {
;                 const int rt = ai * HALF + wr * 64 + m * 16 + fr; const int row = u.pm * BM + rt; float s = 0.f;
; #pragma unroll
;                 for (int bj = 0; bj < 2; ++bj) {
;                     const size_t off = (size_t)row * D + u.pn * BM + bj * HALF + wc * 32 + 8 * fq;
;                     f32x4 b0, b1; unpack8(*(const u32x4*)(base + off), b0, b1);
;                     const f32x4 v0 = b0 + acc[ai][bj][m][0] * scale, v1 = b1 + acc[ai][bj][m][1] * scale;
;                     acc[ai][bj][m][0] = v0; acc[ai][bj][m][1] = v1;
;                     s += (v0[0] * v0[0] + v0[1] * v0[1]) + (v0[2] * v0[2] + v0[3] * v0[3]) + (v1[0] * v1[0] + v1[1] * v1[1]) + (v1[2] * v1[2] + v1[3] * v1[3]);
;                 }
;                 s += __shfl_xor(s, 16); s += __shfl_xor(s, 32);
;                 if (fq == 0) Pw[rt * 4 + wc] = s;
;             }
.LBB0_1906:
	s_or_b64 exec, exec, s[6:7]
	v_add_u32_e32 v148, 0xa0, v167
	v_add_u32_e32 v146, s8, v148
	s_waitcnt lgkmcnt(0)
	v_ashrrev_i32_e32 v147, 31, v146
	v_lshlrev_b64 v[150:151], 11, v[146:147]
	v_lshl_add_u64 v[150:151], s[40:41], 0, v[150:151]
	v_lshl_add_u64 v[150:151], s[2:3], 1, v[150:151]
	v_lshl_add_u64 v[150:151], v[150:151], 0, s[0:1]
	v_mov_b32_e32 v133, 0
	v_lshl_add_u64 v[154:155], v[150:151], 0, v[132:133]
	s_nop 0
	s_waitcnt vmcnt(3)
	v_lshlrev_b32_e32 v158, 16, v236
	v_and_b32_e32 v159, 0xffff0000, v236
	v_lshlrev_b32_e32 v150, 16, v237
	v_and_b32_e32 v151, 0xffff0000, v237
	s_waitcnt vmcnt(2)
	v_lshlrev_b32_e32 v162, 16, v240
	v_and_b32_e32 v163, 0xffff0000, v240
	v_lshlrev_b32_e32 v154, 16, v241
	v_and_b32_e32 v155, 0xffff0000, v241
	v_lshlrev_b32_e32 v160, 16, v238
	v_and_b32_e32 v161, 0xffff0000, v238
	v_lshlrev_b32_e32 v152, 16, v239
	v_and_b32_e32 v153, 0xffff0000, v239
	v_lshlrev_b32_e32 v170, 16, v242
	v_and_b32_e32 v171, 0xffff0000, v242
	v_pk_fma_f32 v[32:33], v[32:33], 0.5, v[150:151] op_sel_hi:[1,0,1]
	v_pk_fma_f32 v[30:31], v[30:31], 0.5, v[158:159] op_sel_hi:[1,0,1]
	v_pk_fma_f32 v[24:25], v[24:25], 0.5, v[154:155] op_sel_hi:[1,0,1]
	v_pk_fma_f32 v[22:23], v[22:23], 0.5, v[162:163] op_sel_hi:[1,0,1]
	v_lshlrev_b32_e32 v156, 16, v243
	v_and_b32_e32 v157, 0xffff0000, v243
	v_pk_fma_f32 v[28:29], v[28:29], 0.5, v[152:153] op_sel_hi:[1,0,1]
	v_pk_fma_f32 v[26:27], v[26:27], 0.5, v[160:161] op_sel_hi:[1,0,1]
	v_pk_fma_f32 v[18:19], v[18:19], 0.5, v[170:171] op_sel_hi:[1,0,1]
	v_mul_f32_e32 v149, v31, v31
	v_mul_f32_e32 v150, v33, v33
	v_mul_f32_e32 v153, v23, v23
	v_mul_f32_e32 v154, v25, v25
	v_pk_fma_f32 v[20:21], v[20:21], 0.5, v[156:157] op_sel_hi:[1,0,1]
	v_mul_f32_e32 v151, v27, v27
	v_mul_f32_e32 v155, v19, v19
	v_fmac_f32_e32 v149, v30, v30
	v_fmac_f32_e32 v150, v32, v32
	v_fmac_f32_e32 v153, v22, v22
	v_fmac_f32_e32 v154, v24, v24
	v_mul_f32_e32 v152, v29, v29
	v_mul_f32_e32 v156, v21, v21
	v_fmac_f32_e32 v151, v26, v26
	v_fmac_f32_e32 v155, v18, v18
	v_add_f32_e32 v149, v149, v150
	v_add_f32_e32 v150, v153, v154
	v_fmac_f32_e32 v152, v28, v28
	v_fmac_f32_e32 v156, v20, v20
	v_add_f32_e32 v149, v151, v149
	v_add_f32_e32 v150, v155, v150
	v_add_f32_e32 v149, v152, v149
	v_add_f32_e32 v150, v156, v150
	v_add_f32_e32 v149, v149, v150
	ds_bpermute_b32 v150, v165, v149
	s_waitcnt lgkmcnt(0)
	v_add_f32_e32 v149, v149, v150
	ds_bpermute_b32 v150, v168, v149
	s_and_saveexec_b64 s[6:7], vcc
	s_cbranch_execz .LBB0_1908
	v_lshl_add_u32 v148, v148, 4, s9
	s_waitcnt lgkmcnt(0)
	v_add_f32_e32 v149, v149, v150
	ds_write_b32 v148, v149
.LBB0_1908:
	s_or_b64 exec, exec, s[6:7]
	v_add_u32_e32 v169, 0xb0, v167
	v_add_u32_e32 v148, s8, v169
	v_ashrrev_i32_e32 v149, 31, v148
	s_waitcnt lgkmcnt(0)
	v_lshlrev_b64 v[150:151], 11, v[148:149]
	v_lshl_add_u64 v[150:151], s[40:41], 0, v[150:151]
	v_lshl_add_u64 v[150:151], s[2:3], 1, v[150:151]
	v_lshl_add_u64 v[150:151], v[150:151], 0, s[0:1]
	v_lshl_add_u64 v[132:133], v[150:151], 0, v[132:133]
	s_waitcnt vmcnt(1)
	v_lshlrev_b32_e32 v132, 16, v244
	v_and_b32_e32 v133, 0xffff0000, v244
	v_lshlrev_b32_e32 v150, 16, v245
	v_and_b32_e32 v151, 0xffff0000, v245
	s_waitcnt vmcnt(0)
	v_lshlrev_b32_e32 v170, 16, v248
	v_and_b32_e32 v171, 0xffff0000, v248
	v_lshlrev_b32_e32 v172, 16, v249
	v_and_b32_e32 v173, 0xffff0000, v249
	v_lshlrev_b32_e32 v158, 16, v246
	v_and_b32_e32 v159, 0xffff0000, v246
	v_lshlrev_b32_e32 v152, 16, v247
	v_and_b32_e32 v153, 0xffff0000, v247
	v_lshlrev_b32_e32 v174, 16, v250
	v_and_b32_e32 v175, 0xffff0000, v250
	v_lshlrev_b32_e32 v176, 16, v251
	v_and_b32_e32 v177, 0xffff0000, v251
	v_pk_fma_f32 v[160:161], v[16:17], 0.5, v[150:151] op_sel_hi:[1,0,1]
	v_pk_fma_f32 v[162:163], v[14:15], 0.5, v[132:133] op_sel_hi:[1,0,1]
	v_pk_fma_f32 v[150:151], v[8:9], 0.5, v[172:173] op_sel_hi:[1,0,1]
	v_pk_fma_f32 v[156:157], v[6:7], 0.5, v[170:171] op_sel_hi:[1,0,1]
	v_pk_fma_f32 v[154:155], v[12:13], 0.5, v[152:153] op_sel_hi:[1,0,1]
	v_pk_fma_f32 v[158:159], v[10:11], 0.5, v[158:159] op_sel_hi:[1,0,1]
	v_pk_fma_f32 v[152:153], v[2:3], 0.5, v[174:175] op_sel_hi:[1,0,1]
	v_mul_f32_e32 v2, v163, v163
	v_mul_f32_e32 v3, v161, v161
	v_mul_f32_e32 v6, v157, v157
	v_mul_f32_e32 v7, v151, v151
	v_pk_fma_f32 v[132:133], v[4:5], 0.5, v[176:177] op_sel_hi:[1,0,1]
	v_mul_f32_e32 v4, v159, v159
	v_mul_f32_e32 v8, v153, v153
	v_fmac_f32_e32 v2, v162, v162
	v_fmac_f32_e32 v3, v160, v160
	v_fmac_f32_e32 v6, v156, v156
	v_fmac_f32_e32 v7, v150, v150
	v_mul_f32_e32 v5, v155, v155
	v_mul_f32_e32 v9, v133, v133
	v_fmac_f32_e32 v4, v158, v158
	v_fmac_f32_e32 v8, v152, v152
	v_add_f32_e32 v2, v2, v3
	v_add_f32_e32 v3, v6, v7
	v_fmac_f32_e32 v5, v154, v154
	v_fmac_f32_e32 v9, v132, v132
	v_add_f32_e32 v2, v4, v2
	v_add_f32_e32 v3, v8, v3
	v_add_f32_e32 v2, v5, v2
	v_add_f32_e32 v3, v9, v3
	v_add_f32_e32 v2, v2, v3
	ds_bpermute_b32 v3, v165, v2
	s_waitcnt lgkmcnt(0)
	v_add_f32_e32 v2, v2, v3
	ds_bpermute_b32 v3, v168, v2
	s_and_saveexec_b64 s[0:1], vcc
	s_cbranch_execz .LBB0_1910
	v_lshl_add_u32 v4, v169, 4, s9
	s_waitcnt lgkmcnt(0)
	v_add_f32_e32 v2, v2, v3
	ds_write_b32 v4, v2
